# prologue: the per-layer-embedding input f32->bf16 conversion loop processes four grid-strided elements per trip (8 loads in flight per lane instead of 2; 4 latency round trips instead of 16)
# speedup vs baseline: 1.0150x; 1.0033x over previous
.LBB0_77:
	s_or_b64 exec, exec, s[50:51]
	s_mov_b32 s4, 0x200000
	v_cmp_gt_i32_e32 vcc, s4, v2
	s_and_saveexec_b64 s[4:5], vcc
	s_cbranch_execz .LBB0_80
	v_lshl_add_u64 v[4:5], v[2:3], 4, s[78:79]
	s_mov_b64 s[6:7], 0x5f00000
	s_ashr_i32 s47, s46, 31
	v_lshlrev_b32_e32 v6, 1, v24
	v_lshl_add_u64 v[4:5], v[4:5], 0, s[6:7]
	s_lshl_b64 s[6:7], s[46:47], 4
	v_lshl_add_u32 v6, s2, 10, v6
	s_lshl_b32 s10, s86, 10
	s_mov_b64 s[8:9], 0
	s_mov_b32 s11, 0x1fffff
	v_mov_b32_e32 v8, v2
	s_waitcnt lgkmcnt(0)
	s_cmp_lg_u32 s46, 0x20000
	s_cbranch_scc1 .LBB0_79
	s_mov_b32 s47, 4
.Lpcvt_unr:
	v_ashrrev_i32_e32 v7, 31, v6
	v_lshl_add_u64 v[86:87], v[6:7], 4, s[14:15]
	global_load_dwordx4 v[100:103], v[86:87], off
	global_load_dwordx4 v[104:107], v[86:87], off offset:16
	v_add_u32_e32 v88, s10, v6
	v_ashrrev_i32_e32 v89, 31, v88
	v_lshl_add_u64 v[90:91], v[88:89], 4, s[14:15]
	global_load_dwordx4 v[108:111], v[90:91], off
	global_load_dwordx4 v[112:115], v[90:91], off offset:16
	v_add_u32_e32 v88, s10, v88
	v_ashrrev_i32_e32 v89, 31, v88
	v_lshl_add_u64 v[90:91], v[88:89], 4, s[14:15]
	global_load_dwordx4 v[116:119], v[90:91], off
	global_load_dwordx4 v[120:123], v[90:91], off offset:16
	v_add_u32_e32 v88, s10, v88
	v_ashrrev_i32_e32 v89, 31, v88
	v_lshl_add_u64 v[90:91], v[88:89], 4, s[14:15]
	global_load_dwordx4 v[124:127], v[90:91], off
	global_load_dwordx4 v[128:131], v[90:91], off offset:16
	v_add_u32_e32 v6, s10, v88
	s_waitcnt vmcnt(6)
	v_cvt_pk_bf16_f32 v100, v100, v101
	v_cvt_pk_bf16_f32 v101, v102, v103
	v_cvt_pk_bf16_f32 v102, v104, v105
	v_cvt_pk_bf16_f32 v103, v106, v107
	global_store_dwordx4 v[4:5], v[100:103], off
	v_lshl_add_u64 v[4:5], v[4:5], 0, s[6:7]
	s_waitcnt vmcnt(5)
	v_cvt_pk_bf16_f32 v108, v108, v109
	v_cvt_pk_bf16_f32 v109, v110, v111
	v_cvt_pk_bf16_f32 v110, v112, v113
	v_cvt_pk_bf16_f32 v111, v114, v115
	global_store_dwordx4 v[4:5], v[108:111], off
	v_lshl_add_u64 v[4:5], v[4:5], 0, s[6:7]
	s_waitcnt vmcnt(4)
	v_cvt_pk_bf16_f32 v116, v116, v117
	v_cvt_pk_bf16_f32 v117, v118, v119
	v_cvt_pk_bf16_f32 v118, v120, v121
	v_cvt_pk_bf16_f32 v119, v122, v123
	global_store_dwordx4 v[4:5], v[116:119], off
	v_lshl_add_u64 v[4:5], v[4:5], 0, s[6:7]
	s_waitcnt vmcnt(3)
	v_cvt_pk_bf16_f32 v124, v124, v125
	v_cvt_pk_bf16_f32 v125, v126, v127
	v_cvt_pk_bf16_f32 v126, v128, v129
	v_cvt_pk_bf16_f32 v127, v130, v131
	global_store_dwordx4 v[4:5], v[124:127], off
	v_lshl_add_u64 v[4:5], v[4:5], 0, s[6:7]
	s_sub_i32 s47, s47, 1
	s_cmp_lg_u32 s47, 0
	s_cbranch_scc1 .Lpcvt_unr
	s_branch .LBB0_80
